# XCC-local barriers for the P4-P5, P5-P6 and P7-P8 seams (workgroups relabelled by XCC rank from P4 on); P7 epilogue row scalars loaded at unit start
# speedup vs baseline: 1.0328x; 1.0051x over previous
; #define LAS __attribute__((address_space(3)))
; __device__ __forceinline__ unsigned xb_add(unsigned* p, unsigned v) { return __hip_atomic_fetch_add(p, v, __ATOMIC_RELAXED, __HIP_MEMORY_SCOPE_AGENT); }
; __device__ __forceinline__ unsigned xb_xcc_id() { return (unsigned)__builtin_amdgcn_s_getreg((3 << 11) | 20) & 0xFu; }
; __device__ __forceinline__ XcdBarrier xcd_barrier_post(unsigned* bar, volatile LAS unsigned* st) {
;     XcdBarrier b; b.bar = bar; b.x = xb_xcc_id(); b.st = st;
;     if (threadIdx.x == 0) (void)xb_add(&bar[XB_XCNT(b.x)], 1u);
;     return b;
; __global__ void __launch_bounds__(NTHREADS, 2) mk_fwd(Args a) {
;     extern __shared__ __attribute__((aligned(16))) unsigned char lds_raw[];
;     cg::grid_group grid = cg::this_grid();
;     LAS unsigned char* lds = (LAS unsigned char*)lds_raw;
;     const int tid = threadIdx.x, lane = tid & 63, wave = __builtin_amdgcn_readfirstlane(tid >> 6);
;     unsigned char* ws = a.ws;
;     const int G = gridDim.x, c = blockIdx.x;
;     volatile LAS unsigned* MISC = (volatile LAS unsigned*)(lds + MISC_OFF);
;     if (tid < 32) MISC[tid] = 0u;
;     __syncthreads();
;     unsigned* barw = (unsigned*)(ws + WS_BAR);
;     XcdBarrier bar = xcd_barrier_post(barw, MISC + 8);
_Z6mk_fwd4Args:
	s_load_dwordx16 s[44:59], s[0:1], 0x80
	s_load_dword s97, s[0:1], 0xd0
	s_load_dwordx2 s[92:93], s[0:1], 0xc8
	s_add_u32 s6, s0, 0xc8
	v_and_b32_e32 v224, 0x3ff, v0
	s_addc_u32 s7, s1, 0
	v_readfirstlane_b32 s41, v224
	v_cmp_gt_u32_e32 vcc, 32, v224
	s_and_saveexec_b64 s[4:5], vcc
	v_lshl_add_u32 v1, v224, 2, 0
	v_add_u32_e32 v1, 0x23f00, v1
	v_mov_b32_e32 v2, 0
	ds_write_b32 v1, v2
	s_or_b64 exec, exec, s[4:5]
	s_load_dwordx2 s[4:5], s[0:1], 0xc0
	s_waitcnt lgkmcnt(0)
	s_barrier
	s_add_u32 s94, s58, 0xc0000
	s_getreg_b32 s3, hwreg(HW_REG_XCC_ID, 0, 4)
	s_addc_u32 s95, s59, 0
	s_and_b32 s3, s3, 15
	v_cmp_eq_u32_e64 s[24:25], 0, v224
	s_and_saveexec_b64 s[8:9], s[24:25]
	s_cbranch_execz .LBB0_5
	s_mov_b64 s[10:11], exec
	v_mbcnt_lo_u32_b32 v1, s10, 0
	v_mbcnt_hi_u32_b32 v1, s11, v1
	v_cmp_eq_u32_e32 vcc, 0, v1
	s_and_b64 s[12:13], exec, vcc
	s_mov_b64 exec, s[12:13]
	s_cbranch_execz .LBB0_5
	s_lshl_b32 s12, s3, 8
	s_bcnt1_i32_b64 s10, s[10:11]
	v_mov_b32_e32 v1, s12
	v_mov_b32_e32 v2, s10
	global_atomic_add v1, v1, v2, s[94:95] offset:1024 sc0
	s_waitcnt vmcnt(0)
	v_mov_b32_e32 v2, 0x23f30
	ds_write_b32 v2, v1

; __device__ __forceinline__ unsigned xb_ld(unsigned* p)              { return __hip_atomic_load(p, __ATOMIC_RELAXED, __HIP_MEMORY_SCOPE_AGENT); }
; __device__ __forceinline__ void xcd_barrier_complete(unsigned* bar, unsigned x, unsigned& nloc, unsigned& nx) {
;     const unsigned G = gridDim.x * gridDim.y * gridDim.z;
;     unsigned sum, cnt, mine, sp = 0u;
;     for (;;) {
;         sum = 0u; cnt = 0u; mine = 0u;
; #pragma unroll
;         for (unsigned j = 0; j < 16; ++j) { const unsigned c = xb_ld(&bar[XB_XCNT(j)]); sum += c; cnt += (c > 0u) ? 1u : 0u; mine = (j == x) ? c : mine; }
;         if (sum == G) break;
;         __builtin_amdgcn_s_sleep(1);
;         if ((++sp & 255u) == 0u) { if (xb_ld(&bar[XB_TMO])) break; if (sp > XB_SPIN_CAP) { atomicAdd(&bar[XB_TMO], 1u); break; } }
;     }
;     nloc = mine > 0u ? mine : 1u; nx = cnt > 0u ? cnt : 1u;
; }
; __device__ __forceinline__ void xcd_barrier(const XcdBarrier& b) {
;     asm volatile("s_waitcnt vmcnt(0)" ::: "memory");
;     __syncthreads();
;     if (threadIdx.x == 0) {
;         unsigned* bar = b.bar;
;         __builtin_amdgcn_s_waitcnt(0);
;         unsigned nloc = b.st[0], nx = b.st[1];
;         if (nloc == 0u) { xcd_barrier_complete(bar, b.x, nloc, nx); b.st[0] = nloc; b.st[1] = nx; }
.LBB0_120:
	v_min_u32_e32 v17, v15, v0
	v_min3_u32 v17, v17, v1, v2
	v_min3_u32 v17, v17, v3, v4
	v_min3_u32 v17, v17, v5, v6
	s_cmp_eq_u32 s3, 0
	s_cselect_b64 vcc, -1, 0
	s_cmp_eq_u32 s3, 1
	v_cndmask_b32_e32 v16, 0, v15, vcc
	s_cselect_b64 vcc, -1, 0
	s_cmp_eq_u32 s3, 2
	v_cndmask_b32_e32 v16, v16, v0, vcc
	s_cselect_b64 vcc, -1, 0
	s_cmp_eq_u32 s3, 3
	v_cndmask_b32_e32 v16, v16, v1, vcc
	s_cselect_b64 vcc, -1, 0
	s_cmp_eq_u32 s3, 4
	v_cndmask_b32_e32 v16, v16, v2, vcc
	s_cselect_b64 vcc, -1, 0
	s_cmp_eq_u32 s3, 5
	v_cndmask_b32_e32 v16, v16, v3, vcc
	s_cselect_b64 vcc, -1, 0
	s_cmp_eq_u32 s3, 6
	v_cndmask_b32_e32 v16, v16, v4, vcc
	s_cselect_b64 vcc, -1, 0
	s_cmp_eq_u32 s3, 7
	v_cndmask_b32_e32 v16, v16, v5, vcc
	s_cselect_b64 vcc, -1, 0
	s_cmp_eq_u32 s3, 8
	v_cndmask_b32_e32 v16, v16, v6, vcc
	s_cselect_b64 vcc, -1, 0
	s_cmp_eq_u32 s3, 9
	v_cndmask_b32_e32 v16, v16, v7, vcc
	s_cselect_b64 vcc, -1, 0
	s_cmp_eq_u32 s3, 10
	v_cndmask_b32_e32 v16, v16, v8, vcc
	s_cselect_b64 vcc, -1, 0
	s_cmp_eq_u32 s3, 11
	v_cndmask_b32_e32 v16, v16, v9, vcc
	s_cselect_b64 vcc, -1, 0
	s_cmp_eq_u32 s3, 12
	v_cndmask_b32_e32 v16, v16, v10, vcc
	s_cselect_b64 vcc, -1, 0
	s_cmp_eq_u32 s3, 13
	v_cndmask_b32_e32 v16, v16, v11, vcc
	s_cselect_b64 vcc, -1, 0
	s_cmp_eq_u32 s3, 14
	v_cndmask_b32_e32 v16, v16, v12, vcc
	s_cselect_b64 vcc, -1, 0
	s_cmp_eq_u32 s3, 15
	v_cndmask_b32_e32 v16, v16, v13, vcc
	s_cselect_b64 vcc, -1, 0
	v_cndmask_b32_e32 v16, v16, v14, vcc
	v_cmp_ne_u32_e32 vcc, 0, v15
	s_add_i32 s4, 0, 0x23f20
	s_nop 0
	v_cndmask_b32_e64 v15, 0, 1, vcc
	v_cmp_ne_u32_e32 vcc, 0, v0
	s_nop 1
	v_addc_co_u32_e32 v0, vcc, 0, v15, vcc
	v_cmp_ne_u32_e32 vcc, 0, v1
	s_nop 1
	v_cndmask_b32_e64 v1, 0, 1, vcc
	v_cmp_ne_u32_e32 vcc, 0, v2
	v_max_u32_e32 v2, 1, v16
	s_nop 0
	v_addc_co_u32_e32 v0, vcc, v0, v1, vcc
	v_cmp_ne_u32_e32 vcc, 0, v3
	s_nop 1
	v_cndmask_b32_e64 v1, 0, 1, vcc
	v_cmp_ne_u32_e32 vcc, 0, v4
	s_nop 1
	v_addc_co_u32_e32 v0, vcc, v0, v1, vcc
	v_cmp_ne_u32_e32 vcc, 0, v5
	s_nop 1
	v_cndmask_b32_e64 v1, 0, 1, vcc
	v_cmp_ne_u32_e32 vcc, 0, v6
	s_nop 1
	v_addc_co_u32_e32 v0, vcc, v0, v1, vcc
	v_cmp_ne_u32_e32 vcc, 0, v7
	s_nop 1
	v_cndmask_b32_e64 v1, 0, 1, vcc
	v_cmp_ne_u32_e32 vcc, 0, v8
	s_nop 1
	v_addc_co_u32_e32 v0, vcc, v0, v1, vcc
	v_cmp_ne_u32_e32 vcc, 0, v9
	s_nop 1
	v_cndmask_b32_e64 v1, 0, 1, vcc
	v_cmp_ne_u32_e32 vcc, 0, v10
	s_nop 1
	v_addc_co_u32_e32 v0, vcc, v0, v1, vcc
	v_cmp_ne_u32_e32 vcc, 0, v11
	s_nop 1
	v_cndmask_b32_e64 v1, 0, 1, vcc
	v_cmp_ne_u32_e32 vcc, 0, v12
	s_nop 1
	v_addc_co_u32_e32 v0, vcc, v0, v1, vcc
	v_cmp_ne_u32_e32 vcc, 0, v13
	s_nop 1
	v_cndmask_b32_e64 v1, 0, 1, vcc
	v_cmp_ne_u32_e32 vcc, 0, v14
	s_nop 1
	v_addc_co_u32_e32 v0, vcc, v0, v1, vcc
	v_mov_b32_e32 v1, s4
	s_add_i32 s4, 0, 0x23f24
	v_max_u32_e32 v0, 1, v0
	ds_write_b32 v1, v2
	v_mov_b32_e32 v1, s4
	ds_write_b32 v1, v0
	v_cmp_eq_u32_e32 vcc, 32, v17
	s_cmp_eq_u32 s39, 0x100
	s_cselect_b64 s[48:49], -1, 0
	s_nop 3
	s_and_b64 vcc, vcc, s[48:49]
	s_nop 3
	v_cndmask_b32_e64 v17, 0, 1, vcc
	v_mov_b32_e32 v16, 0x23f34
	ds_write_b32 v16, v17

; __global__ void __launch_bounds__(NTHREADS, 2) mk_fwd(Args a) {
;     ...
;     const int G = gridDim.x, c = blockIdx.x;
;     ...
;     { pg8::Gemm g{(const pg8::bf16_t*)(ws + WS_Q), (const pg8::bf16_t*)(ws + WS_W2), NTOK, 2048, DM}; pg8::StaticOrder S; S.init(NTOK, 2048, G, c);
;       EpiGlu E{(bf16*)(ws + WS_U), DM, (float*)(ws + WS_ROWSB)};
;       pg8::gemm_phase<EpiGlu, pg8::StaticOrder, true, true>(lds, g, S, E); }
.LBB0_393:
	s_or_b64 exec, exec, s[0:1]
	v_mov_b32_e32 v0, 0x23f30
	ds_read_b64 v[0:1], v0
	s_waitcnt lgkmcnt(0)
	v_readfirstlane_b32 s100, v0
	v_readfirstlane_b32 s101, v1
	s_nop 3
	s_cmp_eq_u32 s101, 1
	s_cbranch_scc0 .Lxb_norelabel
	s_lshl_b32 s100, s100, 3
	s_or_b32 s2, s100, s3
.Lxb_norelabel:
	s_cmpk_lt_i32 s2, 0x400
	s_cselect_b64 s[4:5], -1, 0
	s_cmpk_gt_i32 s2, 0x3ff
	v_readfirstlane_b32 s6, v224
	s_waitcnt lgkmcnt(0)
	s_barrier
	s_cbranch_scc1 .LBB0_399
	s_ashr_i32 s0, s2, 31
	s_lshr_b32 s0, s0, 29
	s_add_i32 s7, s2, s0
	s_and_b32 s0, s7, -8
	s_sub_i32 s8, s2, s0
	s_cmp_gt_i32 s8, -1
	s_cbranch_scc0 .LBB0_396
	s_lshl_b32 s9, s8, 7
	s_cbranch_execz .LBB0_397
	s_branch .LBB0_398

; __device__ __forceinline__ unsigned xb_ld(unsigned* p)              { return __hip_atomic_load(p, __ATOMIC_RELAXED, __HIP_MEMORY_SCOPE_AGENT); }
; __device__ __forceinline__ unsigned xb_add(unsigned* p, unsigned v) { return __hip_atomic_fetch_add(p, v, __ATOMIC_RELAXED, __HIP_MEMORY_SCOPE_AGENT); }
; #define XB_SPIN(cond, bar) do { unsigned _sp = 0; while (cond) { __builtin_amdgcn_s_sleep(1); \
;     if ((++_sp & 255u) == 0u) { if (xb_ld(&(bar)[XB_TMO])) break; if (_sp > XB_SPIN_CAP) { atomicAdd(&(bar)[XB_TMO], 1u); break; } } } } while (0)
; __device__ __forceinline__ void xcd_barrier(const XcdBarrier& b) {
;     ...
;         const unsigned old = xb_add(&bar[XB_XSUB(b.x)], 1u);
;         const unsigned gen = old / nloc;
;         if (old + 1u == (gen + 1u) * nloc) {
;             __builtin_amdgcn_fence(__ATOMIC_RELEASE, "agent");
;             asm volatile("s_waitcnt vmcnt(0)" ::: "memory");
;             const unsigned og = xb_add(&bar[XB_TOP], 1u);
;             const unsigned tg = og / nx;
;             if (og + 1u == (tg + 1u) * nx) xb_add(&bar[XB_TOPGEN], 1u);
;             else XB_SPIN(xb_ld(&bar[XB_TOPGEN]) == tg, bar);
;             __builtin_amdgcn_fence(__ATOMIC_ACQUIRE, "agent");
;             xb_add(&bar[XB_XGEN(b.x)], 1u);
;             asm volatile("s_waitcnt vmcnt(0)" ::: "memory");
.LBB0_467:
	s_andn2_saveexec_b64 s[8:9], s[8:9]
	s_cbranch_execz .LBB0_487
	s_mov_b64 s[8:9], exec
	s_cmp_eq_u32 s101, 1
	s_cbranch_scc1 .LBB0_484
	buffer_wbl2 sc1
	s_waitcnt lgkmcnt(0)
	s_waitcnt vmcnt(0)
	v_mbcnt_lo_u32_b32 v1, s8, 0
	v_mbcnt_hi_u32_b32 v1, s9, v1
	v_cmp_eq_u32_e32 vcc, 0, v1
	s_and_saveexec_b64 s[12:13], vcc
	s_cbranch_execz .LBB0_470
	s_bcnt1_i32_b64 s8, s[8:9]
	v_mov_b32_e32 v2, 0xc3000
	v_mov_b32_e32 v3, s8
	global_atomic_add v2, v2, v3, s[58:59] offset:1024 sc0

; __device__ __forceinline__ unsigned xb_ld(unsigned* p)              { return __hip_atomic_load(p, __ATOMIC_RELAXED, __HIP_MEMORY_SCOPE_AGENT); }
; __device__ __forceinline__ unsigned xb_add(unsigned* p, unsigned v) { return __hip_atomic_fetch_add(p, v, __ATOMIC_RELAXED, __HIP_MEMORY_SCOPE_AGENT); }
; #define XB_SPIN(cond, bar) do { unsigned _sp = 0; while (cond) { __builtin_amdgcn_s_sleep(1); \
;     if ((++_sp & 255u) == 0u) { if (xb_ld(&(bar)[XB_TMO])) break; if (_sp > XB_SPIN_CAP) { atomicAdd(&(bar)[XB_TMO], 1u); break; } } } } while (0)
; __device__ __forceinline__ void xcd_barrier(const XcdBarrier& b) {
;     ...
;         const unsigned old = xb_add(&bar[XB_XSUB(b.x)], 1u);
;         const unsigned gen = old / nloc;
;         if (old + 1u == (gen + 1u) * nloc) {
;             __builtin_amdgcn_fence(__ATOMIC_RELEASE, "agent");
;             asm volatile("s_waitcnt vmcnt(0)" ::: "memory");
;             const unsigned og = xb_add(&bar[XB_TOP], 1u);
;             const unsigned tg = og / nx;
;             if (og + 1u == (tg + 1u) * nx) xb_add(&bar[XB_TOPGEN], 1u);
;             else XB_SPIN(xb_ld(&bar[XB_TOPGEN]) == tg, bar);
;             __builtin_amdgcn_fence(__ATOMIC_ACQUIRE, "agent");
;             xb_add(&bar[XB_XGEN(b.x)], 1u);
;             asm volatile("s_waitcnt vmcnt(0)" ::: "memory");
.LBB0_543:
	s_andn2_saveexec_b64 s[6:7], s[6:7]
	s_cbranch_execz .LBB0_563
	s_mov_b64 s[6:7], exec
	s_cmp_eq_u32 s101, 1
	s_cbranch_scc1 .LBB0_560
	buffer_wbl2 sc1
	s_waitcnt lgkmcnt(0)
	s_waitcnt vmcnt(0)
	v_mbcnt_lo_u32_b32 v1, s6, 0
	v_mbcnt_hi_u32_b32 v1, s7, v1
	v_cmp_eq_u32_e32 vcc, 0, v1
	s_and_saveexec_b64 s[10:11], vcc
	s_cbranch_execz .LBB0_546
	s_bcnt1_i32_b64 s6, s[6:7]
	v_mov_b32_e32 v2, 0xc3000
	v_mov_b32_e32 v3, s6
	global_atomic_add v2, v2, v3, s[58:59] offset:1024 sc0

; template <class Epi, class Sched, bool ALIGN_EPI = false, bool SP2 = false, bool F16 = false>
; __device__ __forceinline__ void gemm_phase(PG8_LAS unsigned char* lds, const Gemm g, const Sched& S, const Epi& E) {
;     ...
; #pragma unroll
;         for (int a = 0; a < 2; ++a)
; #pragma unroll
;             for (int b = 0; b < 2; ++b)
; #pragma unroll
;                 for (int m = 0; m < 4; ++m)
; #pragma unroll
;                     for (int n = 0; n < 2; ++n) acc[a][b][m][n] = (f32x4){0.f, 0.f, 0.f, 0.f};
;         cur = nxt; cA = nA; cB = nB; ++ui;
;     __device__ __forceinline__ void operator()(const pg8::f32x4 (&acc)[2][2][4][2], const pg8::Unit& u, int wr, int wc, int fr, int fq) const {
;     ...
;         float rsv[8];
; #pragma unroll
;         for (int q = 0; q < 8; ++q) rsv[q] = rowss[row0 + (q >> 2) * 128 + (q & 3) * 16];
;         asm volatile("" : "+v"(rsv[0]), "+v"(rsv[1]), "+v"(rsv[2]), "+v"(rsv[3]), "+v"(rsv[4]), "+v"(rsv[5]), "+v"(rsv[6]), "+v"(rsv[7]));
.LBB0_665:
	s_ashr_i32 s19, s18, 31
	s_lshl_b64 s[20:21], s[18:19], 19
	s_add_u32 s20, s8, s20
	s_addc_u32 s21, s9, s21
	s_and_b64 s[22:23], s[4:5], exec
	s_cselect_b32 s19, s21, s27
	s_cselect_b32 s52, s20, s26
	s_ashr_i32 s17, s16, 31
	s_lshl_b64 s[22:23], s[16:17], 19
	s_add_u32 s22, s33, s22
	s_addc_u32 s23, s34, s23
	s_and_b64 s[30:31], s[4:5], exec
	s_cselect_b32 s17, s23, s29
	s_cselect_b32 s53, s22, s28
	s_add_u32 s26, s26, 0x40080
	s_addc_u32 s27, s27, 0
	s_add_u32 s54, s28, 0x100
	v_lshl_add_u32 v248, s24, 8, v138
	v_ashrrev_i32_e32 v249, 31, v248
	v_lshl_add_u64 v[250:251], v[248:249], 2, s[10:11]
	global_load_dword v240, v[250:251], off
	global_load_dword v241, v[250:251], off offset:64
	global_load_dword v242, v[250:251], off offset:128
	global_load_dword v243, v[250:251], off offset:192
	global_load_dword v244, v[250:251], off offset:512
	global_load_dword v245, v[250:251], off offset:576
	global_load_dword v246, v[250:251], off offset:640
	global_load_dword v247, v[250:251], off offset:704
	v_mov_b32_e32 v0, 0
	s_addc_u32 s55, s29, 0
	s_mov_b32 s60, -2
	v_mov_b32_e32 v1, v0
	v_mov_b32_e32 v2, v0
	v_mov_b32_e32 v3, v0
	v_mov_b32_e32 v8, v0
	v_mov_b32_e32 v9, v0
	v_mov_b32_e32 v10, v0
	v_mov_b32_e32 v11, v0
	v_mov_b32_e32 v16, v0
	v_mov_b32_e32 v17, v0
	v_mov_b32_e32 v18, v0
	v_mov_b32_e32 v19, v0
	v_mov_b32_e32 v24, v0
	v_mov_b32_e32 v25, v0
	v_mov_b32_e32 v26, v0
	v_mov_b32_e32 v27, v0
	v_mov_b32_e32 v32, v0
	v_mov_b32_e32 v33, v0
	v_mov_b32_e32 v34, v0
	v_mov_b32_e32 v35, v0
	v_mov_b32_e32 v40, v0
	v_mov_b32_e32 v41, v0
	v_mov_b32_e32 v42, v0
	v_mov_b32_e32 v43, v0
	v_mov_b32_e32 v48, v0
	v_mov_b32_e32 v49, v0
	v_mov_b32_e32 v50, v0
	v_mov_b32_e32 v51, v0
	v_mov_b32_e32 v56, v0
	v_mov_b32_e32 v57, v0
	v_mov_b32_e32 v58, v0
	v_mov_b32_e32 v59, v0
	v_mov_b32_e32 v4, v0
	v_mov_b32_e32 v5, v0
	v_mov_b32_e32 v6, v0
	v_mov_b32_e32 v7, v0
	v_mov_b32_e32 v12, v0
	v_mov_b32_e32 v13, v0
	v_mov_b32_e32 v14, v0
	v_mov_b32_e32 v15, v0
	v_mov_b32_e32 v20, v0
	v_mov_b32_e32 v21, v0
	v_mov_b32_e32 v22, v0
	v_mov_b32_e32 v23, v0
	v_mov_b32_e32 v28, v0
	v_mov_b32_e32 v29, v0
	v_mov_b32_e32 v30, v0
	v_mov_b32_e32 v31, v0
	v_mov_b32_e32 v36, v0
	v_mov_b32_e32 v37, v0
	v_mov_b32_e32 v38, v0
	v_mov_b32_e32 v39, v0
	v_mov_b32_e32 v44, v0
	v_mov_b32_e32 v45, v0
	v_mov_b32_e32 v46, v0
	v_mov_b32_e32 v47, v0
	v_mov_b32_e32 v52, v0
	v_mov_b32_e32 v53, v0
	v_mov_b32_e32 v54, v0
	v_mov_b32_e32 v55, v0
	v_mov_b32_e32 v60, v0
	v_mov_b32_e32 v61, v0
	v_mov_b32_e32 v62, v0
	v_mov_b32_e32 v63, v0
	v_mov_b32_e32 v64, v0
	v_mov_b32_e32 v65, v0
	v_mov_b32_e32 v66, v0
	v_mov_b32_e32 v67, v0
	v_mov_b32_e32 v72, v0
	v_mov_b32_e32 v73, v0
	v_mov_b32_e32 v74, v0
	v_mov_b32_e32 v75, v0
	v_mov_b32_e32 v80, v0
	v_mov_b32_e32 v81, v0
	v_mov_b32_e32 v82, v0
	v_mov_b32_e32 v83, v0
	v_mov_b32_e32 v88, v0
	v_mov_b32_e32 v89, v0
	v_mov_b32_e32 v90, v0
	v_mov_b32_e32 v91, v0
	v_mov_b32_e32 v96, v0
	v_mov_b32_e32 v97, v0
	v_mov_b32_e32 v98, v0
	v_mov_b32_e32 v99, v0
	v_mov_b32_e32 v104, v0
	v_mov_b32_e32 v105, v0
	v_mov_b32_e32 v106, v0
	v_mov_b32_e32 v107, v0
	v_mov_b32_e32 v120, v0
	v_mov_b32_e32 v121, v0
	v_mov_b32_e32 v122, v0
	v_mov_b32_e32 v123, v0
	v_mov_b32_e32 v124, v0
	v_mov_b32_e32 v125, v0
	v_mov_b32_e32 v126, v0
	v_mov_b32_e32 v127, v0
	v_mov_b32_e32 v68, v0
	v_mov_b32_e32 v69, v0
	v_mov_b32_e32 v70, v0
	v_mov_b32_e32 v71, v0
	v_mov_b32_e32 v76, v0
	v_mov_b32_e32 v77, v0
	v_mov_b32_e32 v78, v0
	v_mov_b32_e32 v79, v0
	v_mov_b32_e32 v84, v0
	v_mov_b32_e32 v85, v0
	v_mov_b32_e32 v86, v0
	v_mov_b32_e32 v87, v0
	v_mov_b32_e32 v92, v0
	v_mov_b32_e32 v93, v0
	v_mov_b32_e32 v94, v0
	v_mov_b32_e32 v95, v0
	v_mov_b32_e32 v100, v0
	v_mov_b32_e32 v101, v0
	v_mov_b32_e32 v102, v0
	v_mov_b32_e32 v103, v0
	v_mov_b32_e32 v108, v0
	v_mov_b32_e32 v109, v0
	v_mov_b32_e32 v110, v0
	v_mov_b32_e32 v111, v0
	v_mov_b32_e32 v112, v0
	v_mov_b32_e32 v113, v0
	v_mov_b32_e32 v114, v0
	v_mov_b32_e32 v115, v0
	v_mov_b32_e32 v116, v0
	v_mov_b32_e32 v117, v0
	v_mov_b32_e32 v118, v0
	v_mov_b32_e32 v119, v0

; __device__ __forceinline__ unsigned cvt_pk(float lo, float hi) { unsigned r; asm volatile("v_cvt_pk_bf16_f32 %0, %1, %2" : "=v"(r) : "v"(lo), "v"(hi)); return r; }
; __device__ __forceinline__ float fast_sigmoid(float v) { return __builtin_amdgcn_rcpf(1.0f + __builtin_amdgcn_exp2f(-1.4426950408889634f * v)); }
;     __device__ __forceinline__ void operator()(const pg8::f32x4 (&acc)[2][2][4][2], const pg8::Unit& u, int wr, int wc, int fr, int fq) const {
;     ...
;         float rsv[8];
; #pragma unroll
;         for (int q = 0; q < 8; ++q) rsv[q] = rowss[row0 + (q >> 2) * 128 + (q & 3) * 16];
;         asm volatile("" : "+v"(rsv[0]), "+v"(rsv[1]), "+v"(rsv[2]), "+v"(rsv[3]), "+v"(rsv[4]), "+v"(rsv[5]), "+v"(rsv[6]), "+v"(rsv[7]));
; #pragma unroll
;         for (int ai = 0; ai < 2; ++ai)
; #pragma unroll
;             for (int m = 0; m < 4; ++m) { const int row = row0 + ai * 128 + m * 16; const float rs = __builtin_amdgcn_rsqf(rsv[ai * 4 + m] * (1.0f / DM) + EPS); float o[8];
; #pragma unroll
;                 for (int n = 0; n < 2; ++n)
; #pragma unroll
;                     for (int e = 0; e < 4; ++e) { const float g = acc[ai][0][m][n][e] * rs, up = acc[ai][1][m][n][e] * rs; o[n * 4 + e] = g * fast_sigmoid(g) * up; }
;                 u32x4 w; w.x = cvt_pk(o[0], o[1]); w.y = cvt_pk(o[2], o[3]); w.z = cvt_pk(o[4], o[5]); w.w = cvt_pk(o[6], o[7]);
;                 *(u32x4*)(O + (size_t)row * ldc + col0) = w; }
.LBB0_669:
	v_lshl_add_u32 v136, s24, 8, v138
	v_pk_mul_f32 v[124:125], v[116:117], v[124:125]
	v_pk_mul_f32 v[126:127], v[118:119], v[126:127]
	v_pk_mul_f32 v[120:121], v[112:113], v[120:121]
	v_pk_mul_f32 v[122:123], v[114:115], v[122:123]
	v_pk_mul_f32 v[104:105], v[108:109], v[104:105]
	v_pk_mul_f32 v[106:107], v[110:111], v[106:107]
	v_pk_mul_f32 v[96:97], v[100:101], v[96:97]
	v_pk_mul_f32 v[98:99], v[102:103], v[98:99]
	v_pk_mul_f32 v[88:89], v[92:93], v[88:89]
	v_pk_mul_f32 v[90:91], v[94:95], v[90:91]
	v_pk_mul_f32 v[80:81], v[84:85], v[80:81]
	v_pk_mul_f32 v[82:83], v[86:87], v[82:83]
	v_pk_mul_f32 v[72:73], v[76:77], v[72:73]
	v_pk_mul_f32 v[74:75], v[78:79], v[74:75]
	v_pk_mul_f32 v[64:65], v[68:69], v[64:65]
	v_pk_mul_f32 v[66:67], v[70:71], v[66:67]
	v_pk_mul_f32 v[56:57], v[60:61], v[56:57]
	v_pk_mul_f32 v[58:59], v[62:63], v[58:59]
	v_pk_mul_f32 v[48:49], v[52:53], v[48:49]
	v_pk_mul_f32 v[50:51], v[54:55], v[50:51]
	v_pk_mul_f32 v[40:41], v[44:45], v[40:41]
	v_pk_mul_f32 v[42:43], v[46:47], v[42:43]
	v_pk_mul_f32 v[32:33], v[36:37], v[32:33]
	v_pk_mul_f32 v[34:35], v[38:39], v[34:35]
	v_pk_mul_f32 v[24:25], v[28:29], v[24:25]
	v_pk_mul_f32 v[26:27], v[30:31], v[26:27]
	v_pk_mul_f32 v[16:17], v[20:21], v[16:17]
	v_pk_mul_f32 v[18:19], v[22:23], v[18:19]
	v_pk_mul_f32 v[8:9], v[12:13], v[8:9]
	v_pk_mul_f32 v[10:11], v[14:15], v[10:11]
	v_pk_mul_f32 v[0:1], v[4:5], v[0:1]
	v_pk_mul_f32 v[2:3], v[6:7], v[2:3]
	v_lshl_or_b32 v150, s51, 7, v140
	v_ashrrev_i32_e32 v151, 31, v150
	v_mov_b64_e32 v[154:155], s[48:49]
	v_mad_i64_i32 v[152:153], s[26:27], v136, s50, v[154:155]
	v_lshlrev_b64 v[150:151], 1, v[150:151]
	s_lshl_b32 s60, s50, 4
	s_mov_b32 s61, 0
	s_mul_i32 s62, s50, 0x50
	s_mov_b32 s63, 0
	v_lshl_add_u64 v[152:153], v[152:153], 0, v[150:151]
	v_fmamk_f32 v180, v240, 0x3a800000, v144
	v_fmamk_f32 v184, v241, 0x3a800000, v144
	v_fmamk_f32 v188, v242, 0x3a800000, v144
	v_fmamk_f32 v192, v243, 0x3a800000, v144
	v_fmamk_f32 v196, v244, 0x3a800000, v144
	v_fmamk_f32 v200, v245, 0x3a800000, v144
	v_fmamk_f32 v204, v246, 0x3a800000, v144
	v_fmamk_f32 v208, v247, 0x3a800000, v144
	v_rsq_f32_e32 v182, v180
	v_rsq_f32_e32 v186, v184
	v_rsq_f32_e32 v190, v188
	v_rsq_f32_e32 v194, v192
	v_rsq_f32_e32 v198, v196
	v_rsq_f32_e32 v202, v200
	v_rsq_f32_e32 v206, v204
	v_rsq_f32_e32 v210, v208
	s_nop 0
	v_mul_f32_e32 v182, 0xbfb8aa3b, v182
	v_mul_f32_e32 v186, 0xbfb8aa3b, v186
	v_mul_f32_e32 v190, 0xbfb8aa3b, v190
	v_mul_f32_e32 v194, 0xbfb8aa3b, v194
	v_mul_f32_e32 v198, 0xbfb8aa3b, v198
	v_mul_f32_e32 v202, 0xbfb8aa3b, v202
	v_mul_f32_e32 v206, 0xbfb8aa3b, v206
	v_mul_f32_e32 v210, 0xbfb8aa3b, v210
	v_pk_mul_f32 v[116:117], v[116:117], v[182:183] op_sel_hi:[1,0]
	v_pk_mul_f32 v[118:119], v[118:119], v[182:183] op_sel_hi:[1,0]
	v_pk_mul_f32 v[112:113], v[112:113], v[182:183] op_sel_hi:[1,0]
	v_pk_mul_f32 v[114:115], v[114:115], v[182:183] op_sel_hi:[1,0]
	v_exp_f32_e32 v116, v116
	v_exp_f32_e32 v117, v117
	v_exp_f32_e32 v118, v118
	v_exp_f32_e32 v119, v119
	v_exp_f32_e32 v112, v112
	v_exp_f32_e32 v113, v113
	v_exp_f32_e32 v114, v114
	v_exp_f32_e32 v115, v115
	v_pk_fma_f32 v[116:117], v[116:117], v[180:181], v[180:181] op_sel_hi:[1,0,0]
	v_pk_fma_f32 v[118:119], v[118:119], v[180:181], v[180:181] op_sel_hi:[1,0,0]
	v_pk_fma_f32 v[112:113], v[112:113], v[180:181], v[180:181] op_sel_hi:[1,0,0]
	v_pk_fma_f32 v[114:115], v[114:115], v[180:181], v[180:181] op_sel_hi:[1,0,0]
	v_rcp_f32_e32 v116, v116
	v_rcp_f32_e32 v117, v117
	v_rcp_f32_e32 v118, v118
	v_rcp_f32_e32 v119, v119
	v_rcp_f32_e32 v112, v112
	v_rcp_f32_e32 v113, v113
	v_rcp_f32_e32 v114, v114
	v_rcp_f32_e32 v115, v115
	v_pk_mul_f32 v[124:125], v[124:125], v[116:117]
	v_pk_mul_f32 v[126:127], v[126:127], v[118:119]
	v_pk_mul_f32 v[120:121], v[120:121], v[112:113]
	v_pk_mul_f32 v[122:123], v[122:123], v[114:115]
	v_cvt_pk_bf16_f32 v116, v124, v125
	v_cvt_pk_bf16_f32 v117, v126, v127
	v_cvt_pk_bf16_f32 v118, v120, v121
	v_cvt_pk_bf16_f32 v119, v122, v123
	global_store_dwordx4 v[152:153], v[116:119], off
	v_pk_mul_f32 v[108:109], v[108:109], v[186:187] op_sel_hi:[1,0]
	v_pk_mul_f32 v[110:111], v[110:111], v[186:187] op_sel_hi:[1,0]
	v_pk_mul_f32 v[100:101], v[100:101], v[186:187] op_sel_hi:[1,0]
	v_pk_mul_f32 v[102:103], v[102:103], v[186:187] op_sel_hi:[1,0]
	v_exp_f32_e32 v108, v108
	v_exp_f32_e32 v109, v109
	v_exp_f32_e32 v110, v110
	v_exp_f32_e32 v111, v111
	v_exp_f32_e32 v100, v100
	v_exp_f32_e32 v101, v101
	v_exp_f32_e32 v102, v102
	v_exp_f32_e32 v103, v103
	v_pk_fma_f32 v[108:109], v[108:109], v[184:185], v[184:185] op_sel_hi:[1,0,0]
	v_pk_fma_f32 v[110:111], v[110:111], v[184:185], v[184:185] op_sel_hi:[1,0,0]
	v_pk_fma_f32 v[100:101], v[100:101], v[184:185], v[184:185] op_sel_hi:[1,0,0]
	v_pk_fma_f32 v[102:103], v[102:103], v[184:185], v[184:185] op_sel_hi:[1,0,0]
	v_rcp_f32_e32 v108, v108
	v_rcp_f32_e32 v109, v109
	v_rcp_f32_e32 v110, v110
	v_rcp_f32_e32 v111, v111
	v_rcp_f32_e32 v100, v100
	v_rcp_f32_e32 v101, v101
	v_rcp_f32_e32 v102, v102
	v_rcp_f32_e32 v103, v103
	v_pk_mul_f32 v[104:105], v[104:105], v[108:109]
	v_pk_mul_f32 v[106:107], v[106:107], v[110:111]
	v_pk_mul_f32 v[96:97], v[96:97], v[100:101]
	v_pk_mul_f32 v[98:99], v[98:99], v[102:103]
	v_lshl_add_u64 v[152:153], v[152:153], 0, s[60:61]
	v_cvt_pk_bf16_f32 v108, v104, v105
	v_cvt_pk_bf16_f32 v109, v106, v107
	v_cvt_pk_bf16_f32 v110, v96, v97
	v_cvt_pk_bf16_f32 v111, v98, v99
	global_store_dwordx4 v[152:153], v[108:111], off
	v_pk_mul_f32 v[92:93], v[92:93], v[190:191] op_sel_hi:[1,0]
	v_pk_mul_f32 v[94:95], v[94:95], v[190:191] op_sel_hi:[1,0]
	v_pk_mul_f32 v[84:85], v[84:85], v[190:191] op_sel_hi:[1,0]
; __device__ __forceinline__ unsigned cvt_pk(float lo, float hi) { unsigned r; asm volatile("v_cvt_pk_bf16_f32 %0, %1, %2" : "=v"(r) : "v"(lo), "v"(hi)); return r; }
; __device__ __forceinline__ float fast_sigmoid(float v) { return __builtin_amdgcn_rcpf(1.0f + __builtin_amdgcn_exp2f(-1.4426950408889634f * v)); }
;     __device__ __forceinline__ void operator()(const pg8::f32x4 (&acc)[2][2][4][2], const pg8::Unit& u, int wr, int wc, int fr, int fq) const {
;     ...
;         for (int ai = 0; ai < 2; ++ai)
; #pragma unroll
;             for (int m = 0; m < 4; ++m) { const int row = row0 + ai * 128 + m * 16; const float rs = __builtin_amdgcn_rsqf(rsv[ai * 4 + m] * (1.0f / DM) + EPS); float o[8];
; #pragma unroll
;                 for (int n = 0; n < 2; ++n)
; #pragma unroll
;                     for (int e = 0; e < 4; ++e) { const float g = acc[ai][0][m][n][e] * rs, up = acc[ai][1][m][n][e] * rs; o[n * 4 + e] = g * fast_sigmoid(g) * up; }
;                 u32x4 w; w.x = cvt_pk(o[0], o[1]); w.y = cvt_pk(o[2], o[3]); w.z = cvt_pk(o[4], o[5]); w.w = cvt_pk(o[6], o[7]);
;                 *(u32x4*)(O + (size_t)row * ldc + col0) = w; }
	v_pk_mul_f32 v[86:87], v[86:87], v[190:191] op_sel_hi:[1,0]
	v_exp_f32_e32 v92, v92
	v_exp_f32_e32 v93, v93
	v_exp_f32_e32 v94, v94
	v_exp_f32_e32 v95, v95
	v_exp_f32_e32 v84, v84
	v_exp_f32_e32 v85, v85
	v_exp_f32_e32 v86, v86
	v_exp_f32_e32 v87, v87
	v_pk_fma_f32 v[92:93], v[92:93], v[188:189], v[188:189] op_sel_hi:[1,0,0]
	v_pk_fma_f32 v[94:95], v[94:95], v[188:189], v[188:189] op_sel_hi:[1,0,0]
	v_pk_fma_f32 v[84:85], v[84:85], v[188:189], v[188:189] op_sel_hi:[1,0,0]
	v_pk_fma_f32 v[86:87], v[86:87], v[188:189], v[188:189] op_sel_hi:[1,0,0]
	v_rcp_f32_e32 v92, v92
	v_rcp_f32_e32 v93, v93
	v_rcp_f32_e32 v94, v94
	v_rcp_f32_e32 v95, v95
	v_rcp_f32_e32 v84, v84
	v_rcp_f32_e32 v85, v85
	v_rcp_f32_e32 v86, v86
	v_rcp_f32_e32 v87, v87
	v_pk_mul_f32 v[88:89], v[88:89], v[92:93]
	v_pk_mul_f32 v[90:91], v[90:91], v[94:95]
	v_pk_mul_f32 v[80:81], v[80:81], v[84:85]
	v_pk_mul_f32 v[82:83], v[82:83], v[86:87]
	v_lshl_add_u64 v[152:153], v[152:153], 0, s[60:61]
	v_cvt_pk_bf16_f32 v92, v88, v89
	v_cvt_pk_bf16_f32 v93, v90, v91
	v_cvt_pk_bf16_f32 v94, v80, v81
	v_cvt_pk_bf16_f32 v95, v82, v83
	global_store_dwordx4 v[152:153], v[92:95], off
	v_pk_mul_f32 v[76:77], v[76:77], v[194:195] op_sel_hi:[1,0]
	v_pk_mul_f32 v[78:79], v[78:79], v[194:195] op_sel_hi:[1,0]
	v_pk_mul_f32 v[68:69], v[68:69], v[194:195] op_sel_hi:[1,0]
	v_pk_mul_f32 v[70:71], v[70:71], v[194:195] op_sel_hi:[1,0]
	v_exp_f32_e32 v76, v76
	v_exp_f32_e32 v77, v77
	v_exp_f32_e32 v78, v78
	v_exp_f32_e32 v79, v79
	v_exp_f32_e32 v68, v68
	v_exp_f32_e32 v69, v69
	v_exp_f32_e32 v70, v70
	v_exp_f32_e32 v71, v71
	v_pk_fma_f32 v[76:77], v[76:77], v[192:193], v[192:193] op_sel_hi:[1,0,0]
	v_pk_fma_f32 v[78:79], v[78:79], v[192:193], v[192:193] op_sel_hi:[1,0,0]
	v_pk_fma_f32 v[68:69], v[68:69], v[192:193], v[192:193] op_sel_hi:[1,0,0]
	v_pk_fma_f32 v[70:71], v[70:71], v[192:193], v[192:193] op_sel_hi:[1,0,0]
	v_rcp_f32_e32 v76, v76
	v_rcp_f32_e32 v77, v77
	v_rcp_f32_e32 v78, v78
	v_rcp_f32_e32 v79, v79
	v_rcp_f32_e32 v68, v68
	v_rcp_f32_e32 v69, v69
	v_rcp_f32_e32 v70, v70
	v_rcp_f32_e32 v71, v71
	v_pk_mul_f32 v[72:73], v[72:73], v[76:77]
	v_pk_mul_f32 v[74:75], v[74:75], v[78:79]
	v_pk_mul_f32 v[64:65], v[64:65], v[68:69]
	v_pk_mul_f32 v[66:67], v[66:67], v[70:71]
	v_lshl_add_u64 v[152:153], v[152:153], 0, s[60:61]
	v_cvt_pk_bf16_f32 v76, v72, v73
	v_cvt_pk_bf16_f32 v77, v74, v75
	v_cvt_pk_bf16_f32 v78, v64, v65
	v_cvt_pk_bf16_f32 v79, v66, v67
	global_store_dwordx4 v[152:153], v[76:79], off
	v_pk_mul_f32 v[60:61], v[60:61], v[198:199] op_sel_hi:[1,0]
	v_pk_mul_f32 v[62:63], v[62:63], v[198:199] op_sel_hi:[1,0]
	v_pk_mul_f32 v[52:53], v[52:53], v[198:199] op_sel_hi:[1,0]
	v_pk_mul_f32 v[54:55], v[54:55], v[198:199] op_sel_hi:[1,0]
	v_exp_f32_e32 v60, v60
	v_exp_f32_e32 v61, v61
	v_exp_f32_e32 v62, v62
	v_exp_f32_e32 v63, v63
	v_exp_f32_e32 v52, v52
	v_exp_f32_e32 v53, v53
	v_exp_f32_e32 v54, v54
	v_exp_f32_e32 v55, v55
	v_pk_fma_f32 v[60:61], v[60:61], v[196:197], v[196:197] op_sel_hi:[1,0,0]
	v_pk_fma_f32 v[62:63], v[62:63], v[196:197], v[196:197] op_sel_hi:[1,0,0]
	v_pk_fma_f32 v[52:53], v[52:53], v[196:197], v[196:197] op_sel_hi:[1,0,0]
	v_pk_fma_f32 v[54:55], v[54:55], v[196:197], v[196:197] op_sel_hi:[1,0,0]
	v_rcp_f32_e32 v60, v60
	v_rcp_f32_e32 v61, v61
	v_rcp_f32_e32 v62, v62
	v_rcp_f32_e32 v63, v63
	v_rcp_f32_e32 v52, v52
	v_rcp_f32_e32 v53, v53
	v_rcp_f32_e32 v54, v54
	v_rcp_f32_e32 v55, v55
	v_pk_mul_f32 v[56:57], v[56:57], v[60:61]
	v_pk_mul_f32 v[58:59], v[58:59], v[62:63]
	v_pk_mul_f32 v[48:49], v[48:49], v[52:53]
	v_pk_mul_f32 v[50:51], v[50:51], v[54:55]
	v_lshl_add_u64 v[152:153], v[152:153], 0, s[62:63]
	v_cvt_pk_bf16_f32 v60, v56, v57
	v_cvt_pk_bf16_f32 v61, v58, v59
	v_cvt_pk_bf16_f32 v62, v48, v49
	v_cvt_pk_bf16_f32 v63, v50, v51
	global_store_dwordx4 v[152:153], v[60:63], off
	v_pk_mul_f32 v[44:45], v[44:45], v[202:203] op_sel_hi:[1,0]
	v_pk_mul_f32 v[46:47], v[46:47], v[202:203] op_sel_hi:[1,0]
; __device__ __forceinline__ unsigned cvt_pk(float lo, float hi) { unsigned r; asm volatile("v_cvt_pk_bf16_f32 %0, %1, %2" : "=v"(r) : "v"(lo), "v"(hi)); return r; }
; __device__ __forceinline__ float fast_sigmoid(float v) { return __builtin_amdgcn_rcpf(1.0f + __builtin_amdgcn_exp2f(-1.4426950408889634f * v)); }
;     __device__ __forceinline__ void operator()(const pg8::f32x4 (&acc)[2][2][4][2], const pg8::Unit& u, int wr, int wc, int fr, int fq) const {
;     ...
;         for (int ai = 0; ai < 2; ++ai)
; #pragma unroll
;             for (int m = 0; m < 4; ++m) { const int row = row0 + ai * 128 + m * 16; const float rs = __builtin_amdgcn_rsqf(rsv[ai * 4 + m] * (1.0f / DM) + EPS); float o[8];
; #pragma unroll
;                 for (int n = 0; n < 2; ++n)
; #pragma unroll
;                     for (int e = 0; e < 4; ++e) { const float g = acc[ai][0][m][n][e] * rs, up = acc[ai][1][m][n][e] * rs; o[n * 4 + e] = g * fast_sigmoid(g) * up; }
;                 u32x4 w; w.x = cvt_pk(o[0], o[1]); w.y = cvt_pk(o[2], o[3]); w.z = cvt_pk(o[4], o[5]); w.w = cvt_pk(o[6], o[7]);
;                 *(u32x4*)(O + (size_t)row * ldc + col0) = w; }
	v_pk_mul_f32 v[36:37], v[36:37], v[202:203] op_sel_hi:[1,0]
	v_pk_mul_f32 v[38:39], v[38:39], v[202:203] op_sel_hi:[1,0]
	v_exp_f32_e32 v44, v44
	v_exp_f32_e32 v45, v45
	v_exp_f32_e32 v46, v46
	v_exp_f32_e32 v47, v47
	v_exp_f32_e32 v36, v36
	v_exp_f32_e32 v37, v37
	v_exp_f32_e32 v38, v38
	v_exp_f32_e32 v39, v39
	v_pk_fma_f32 v[44:45], v[44:45], v[200:201], v[200:201] op_sel_hi:[1,0,0]
	v_pk_fma_f32 v[46:47], v[46:47], v[200:201], v[200:201] op_sel_hi:[1,0,0]
	v_pk_fma_f32 v[36:37], v[36:37], v[200:201], v[200:201] op_sel_hi:[1,0,0]
	v_pk_fma_f32 v[38:39], v[38:39], v[200:201], v[200:201] op_sel_hi:[1,0,0]
	v_rcp_f32_e32 v44, v44
	v_rcp_f32_e32 v45, v45
	v_rcp_f32_e32 v46, v46
	v_rcp_f32_e32 v47, v47
	v_rcp_f32_e32 v36, v36
	v_rcp_f32_e32 v37, v37
	v_rcp_f32_e32 v38, v38
	v_rcp_f32_e32 v39, v39
	v_pk_mul_f32 v[40:41], v[40:41], v[44:45]
	v_pk_mul_f32 v[42:43], v[42:43], v[46:47]
	v_pk_mul_f32 v[32:33], v[32:33], v[36:37]
	v_pk_mul_f32 v[34:35], v[34:35], v[38:39]
	v_lshl_add_u64 v[152:153], v[152:153], 0, s[60:61]
	v_cvt_pk_bf16_f32 v44, v40, v41
	v_cvt_pk_bf16_f32 v45, v42, v43
	v_cvt_pk_bf16_f32 v46, v32, v33
	v_cvt_pk_bf16_f32 v47, v34, v35
	global_store_dwordx4 v[152:153], v[44:47], off
	v_pk_mul_f32 v[28:29], v[28:29], v[206:207] op_sel_hi:[1,0]
	v_pk_mul_f32 v[30:31], v[30:31], v[206:207] op_sel_hi:[1,0]
	v_pk_mul_f32 v[20:21], v[20:21], v[206:207] op_sel_hi:[1,0]
	v_pk_mul_f32 v[22:23], v[22:23], v[206:207] op_sel_hi:[1,0]
	v_exp_f32_e32 v28, v28
	v_exp_f32_e32 v29, v29
	v_exp_f32_e32 v30, v30
	v_exp_f32_e32 v31, v31
	v_exp_f32_e32 v20, v20
	v_exp_f32_e32 v21, v21
	v_exp_f32_e32 v22, v22
	v_exp_f32_e32 v23, v23
	v_pk_fma_f32 v[28:29], v[28:29], v[204:205], v[204:205] op_sel_hi:[1,0,0]
	v_pk_fma_f32 v[30:31], v[30:31], v[204:205], v[204:205] op_sel_hi:[1,0,0]
	v_pk_fma_f32 v[20:21], v[20:21], v[204:205], v[204:205] op_sel_hi:[1,0,0]
	v_pk_fma_f32 v[22:23], v[22:23], v[204:205], v[204:205] op_sel_hi:[1,0,0]
	v_rcp_f32_e32 v28, v28
	v_rcp_f32_e32 v29, v29
	v_rcp_f32_e32 v30, v30
	v_rcp_f32_e32 v31, v31
	v_rcp_f32_e32 v20, v20
	v_rcp_f32_e32 v21, v21
	v_rcp_f32_e32 v22, v22
	v_rcp_f32_e32 v23, v23
	v_pk_mul_f32 v[24:25], v[24:25], v[28:29]
	v_pk_mul_f32 v[26:27], v[26:27], v[30:31]
	v_pk_mul_f32 v[16:17], v[16:17], v[20:21]
	v_pk_mul_f32 v[18:19], v[18:19], v[22:23]
	v_lshl_add_u64 v[152:153], v[152:153], 0, s[60:61]
	v_cvt_pk_bf16_f32 v28, v24, v25
	v_cvt_pk_bf16_f32 v29, v26, v27
	v_cvt_pk_bf16_f32 v30, v16, v17
	v_cvt_pk_bf16_f32 v31, v18, v19
	global_store_dwordx4 v[152:153], v[28:31], off
	v_pk_mul_f32 v[12:13], v[12:13], v[210:211] op_sel_hi:[1,0]
	v_pk_mul_f32 v[14:15], v[14:15], v[210:211] op_sel_hi:[1,0]
	v_pk_mul_f32 v[4:5], v[4:5], v[210:211] op_sel_hi:[1,0]
	v_pk_mul_f32 v[6:7], v[6:7], v[210:211] op_sel_hi:[1,0]
	v_exp_f32_e32 v12, v12
	v_exp_f32_e32 v13, v13
	v_exp_f32_e32 v14, v14
	v_exp_f32_e32 v15, v15
	v_exp_f32_e32 v4, v4
	v_exp_f32_e32 v5, v5
	v_exp_f32_e32 v6, v6
	v_exp_f32_e32 v7, v7
	v_pk_fma_f32 v[12:13], v[12:13], v[208:209], v[208:209] op_sel_hi:[1,0,0]
	v_pk_fma_f32 v[14:15], v[14:15], v[208:209], v[208:209] op_sel_hi:[1,0,0]
	v_pk_fma_f32 v[4:5], v[4:5], v[208:209], v[208:209] op_sel_hi:[1,0,0]
	v_pk_fma_f32 v[6:7], v[6:7], v[208:209], v[208:209] op_sel_hi:[1,0,0]
	v_rcp_f32_e32 v12, v12
	v_rcp_f32_e32 v13, v13
	v_rcp_f32_e32 v14, v14
	v_rcp_f32_e32 v15, v15
	v_rcp_f32_e32 v4, v4
	v_rcp_f32_e32 v5, v5
	v_rcp_f32_e32 v6, v6
	v_rcp_f32_e32 v7, v7
	v_pk_mul_f32 v[8:9], v[8:9], v[12:13]
	v_pk_mul_f32 v[10:11], v[10:11], v[14:15]
	v_pk_mul_f32 v[0:1], v[0:1], v[4:5]
	v_pk_mul_f32 v[2:3], v[2:3], v[6:7]
	v_lshl_add_u64 v[152:153], v[152:153], 0, s[60:61]
	v_cvt_pk_bf16_f32 v12, v8, v9
	v_cvt_pk_bf16_f32 v13, v10, v11
	v_cvt_pk_bf16_f32 v14, v0, v1
	v_cvt_pk_bf16_f32 v15, v2, v3
	global_store_dwordx4 v[152:153], v[12:15], off
	s_andn2_b64 vcc, exec, s[4:5]
	s_mov_b64 s[4:5], -1
	s_cbranch_vccnz .LBB0_662
	s_andn2_b64 vcc, exec, s[6:7]
	s_cbranch_vccnz .LBB0_661
	s_barrier
	s_branch .LBB0_661

; __device__ __forceinline__ unsigned xb_ld(unsigned* p)              { return __hip_atomic_load(p, __ATOMIC_RELAXED, __HIP_MEMORY_SCOPE_AGENT); }
; __device__ __forceinline__ unsigned xb_add(unsigned* p, unsigned v) { return __hip_atomic_fetch_add(p, v, __ATOMIC_RELAXED, __HIP_MEMORY_SCOPE_AGENT); }
; #define XB_SPIN(cond, bar) do { unsigned _sp = 0; while (cond) { __builtin_amdgcn_s_sleep(1); \
;     if ((++_sp & 255u) == 0u) { if (xb_ld(&(bar)[XB_TMO])) break; if (_sp > XB_SPIN_CAP) { atomicAdd(&(bar)[XB_TMO], 1u); break; } } } } while (0)
; __device__ __forceinline__ void xcd_barrier(const XcdBarrier& b) {
;     ...
;         const unsigned old = xb_add(&bar[XB_XSUB(b.x)], 1u);
;         const unsigned gen = old / nloc;
;         if (old + 1u == (gen + 1u) * nloc) {
;             __builtin_amdgcn_fence(__ATOMIC_RELEASE, "agent");
;             asm volatile("s_waitcnt vmcnt(0)" ::: "memory");
;             const unsigned og = xb_add(&bar[XB_TOP], 1u);
;             const unsigned tg = og / nx;
;             if (og + 1u == (tg + 1u) * nx) xb_add(&bar[XB_TOPGEN], 1u);
;             else XB_SPIN(xb_ld(&bar[XB_TOPGEN]) == tg, bar);
;             __builtin_amdgcn_fence(__ATOMIC_ACQUIRE, "agent");
;             xb_add(&bar[XB_XGEN(b.x)], 1u);
;             asm volatile("s_waitcnt vmcnt(0)" ::: "memory");
.LBB0_705:
	s_andn2_saveexec_b64 s[10:11], s[10:11]
	s_cbranch_execz .LBB0_725
	s_mov_b64 s[10:11], exec
	s_cmp_eq_u32 s101, 1
	s_cbranch_scc1 .LBB0_722
	buffer_wbl2 sc1
	s_waitcnt lgkmcnt(0)
	s_waitcnt vmcnt(0)
	v_mbcnt_lo_u32_b32 v1, s10, 0
	v_mbcnt_hi_u32_b32 v1, s11, v1
	v_cmp_eq_u32_e32 vcc, 0, v1
	s_and_saveexec_b64 s[12:13], vcc
	s_cbranch_execz .LBB0_708
	s_bcnt1_i32_b64 s3, s[10:11]
	v_mov_b32_e32 v2, 0xc3000
	v_mov_b32_e32 v3, s3
	global_atomic_add v2, v2, v3, s[58:59] offset:1024 sc0
